# stack: SwiGLU fma form + K-loop back-edge rotation and hoisted B read bases (proj, gate-up) + XCD leader invalidate beside its write-back
# baseline (speedup 1.0000x reference)
.LBB0_1063:
	v_add_u32_e32 v133, 0x10000, v163
	s_add_i32 s71, s71, 1
	s_cmp_gt_u32 s71, 1
	s_cselect_b32 s32, 1, 0
	s_cmp_lt_u32 s71, 11
	s_cselect_b64 s[36:37], -1, 0
	s_add_i32 s24, s4, 4
	s_mov_b32 s26, s42
.LBB0_1065:
	s_ashr_i32 s27, s26, 31
	s_lshl_b64 s[6:7], s[26:27], 20
	s_add_u32 s38, s52, s6
	s_addc_u32 s39, s53, s7
	s_and_b64 s[6:7], s[36:37], exec
	s_cselect_b32 s5, s39, s47
	s_cselect_b32 s6, s38, s46
	s_ashr_i32 s25, s24, 31
	s_lshl_b64 s[8:9], s[24:25], 20
	s_add_u32 s40, s54, s8
	s_addc_u32 s41, s55, s9
	s_and_b64 s[8:9], s[36:37], exec
	s_cselect_b32 s7, s41, s45
	s_cselect_b32 s8, s40, s44
	s_add_u32 s9, s44, 0x100
	s_addc_u32 s10, s45, 0
	s_add_u32 s44, s46, 0x80080
	s_addc_u32 s45, s47, 0
	s_mov_b32 s11, -2
	s_add_u32 s12, s44, 0xfff80080
	s_addc_u32 s13, s45, -1
	s_add_i32 s14, 0, 0x10000
	s_cmp_eq_u32 s11, 28
	s_cselect_b32 s49, s5, s13
	s_cselect_b32 s48, s6, s12
	s_cselect_b32 s47, s7, s10
	s_cselect_b32 s46, s8, s9
	s_add_i32 s15, 0, 0x14000
	ds_read_b128 v[142:145], v133
	ds_read_b128 v[146:149], v133 offset:1024
	ds_read_b128 v[150:153], v133 offset:2048
	ds_read_b128 v[154:157], v133 offset:3072
	ds_read_b128 v[168:171], v133 offset:16384
	ds_read_b128 v[172:175], v133 offset:17408
	ds_read_b128 v[176:179], v133 offset:18432
	ds_read_b128 v[180:183], v133 offset:19456
	s_add_i32 m0, s60, 0xc000
	ds_read_b128 v[184:187], v167
	ds_read_b128 v[188:191], v167 offset:1024
	ds_read_b128 v[192:195], v167 offset:2048
	ds_read_b128 v[196:199], v167 offset:3072
	ds_read_b128 v[200:203], v167 offset:4096
	ds_read_b128 v[204:207], v167 offset:5120
	ds_read_b128 v[208:211], v167 offset:6144
	ds_read_b128 v[212:215], v167 offset:7168
	global_load_lds_dwordx4 v140, s[44:45]
	s_add_i32 m0, s60, 0xe000
	s_nop 0
	global_load_lds_dwordx4 v138, s[44:45]
	s_cmp_lg_u32 s32, 0
	s_cbranch_scc1 .Lgu_skip1_p
	s_waitcnt vmcnt(8)

.Lgu_skip2_p:
	s_mov_b32 s32, 0
	s_waitcnt lgkmcnt(0)
	s_barrier
	s_setprio 1
	s_waitcnt lgkmcnt(0)
	v_mfma_f32_16x16x32_bf16 v[64:67], v[142:145], v[184:187], 0
	v_mfma_f32_16x16x32_bf16 v[56:59], v[150:153], v[184:187], 0
	v_mfma_f32_16x16x32_bf16 v[48:51], v[142:145], v[192:195], 0
	v_mfma_f32_16x16x32_bf16 v[40:43], v[150:153], v[192:195], 0
	v_mfma_f32_16x16x32_bf16 v[32:35], v[142:145], v[200:203], 0
	v_mfma_f32_16x16x32_bf16 v[24:27], v[150:153], v[200:203], 0
	v_mfma_f32_16x16x32_bf16 v[16:19], v[142:145], v[208:211], 0
	v_mfma_f32_16x16x32_bf16 v[8:11], v[150:153], v[208:211], 0
	v_mfma_f32_16x16x32_bf16 v[64:67], v[146:149], v[188:191], v[64:67]
	v_mfma_f32_16x16x32_bf16 v[56:59], v[154:157], v[188:191], v[56:59]
	v_mfma_f32_16x16x32_bf16 v[48:51], v[146:149], v[196:199], v[48:51]
	v_mfma_f32_16x16x32_bf16 v[40:43], v[154:157], v[196:199], v[40:43]
	v_mfma_f32_16x16x32_bf16 v[32:35], v[146:149], v[204:207], v[32:35]
	v_mfma_f32_16x16x32_bf16 v[24:27], v[154:157], v[204:207], v[24:27]
	v_mfma_f32_16x16x32_bf16 v[16:19], v[146:149], v[212:215], v[16:19]
	v_mfma_f32_16x16x32_bf16 v[8:11], v[154:157], v[212:215], v[8:11]
	v_mfma_f32_16x16x32_bf16 v[60:63], v[168:171], v[184:187], 0
	v_mfma_f32_16x16x32_bf16 v[52:55], v[176:179], v[184:187], 0
	v_mfma_f32_16x16x32_bf16 v[44:47], v[168:171], v[192:195], 0
	v_mfma_f32_16x16x32_bf16 v[36:39], v[176:179], v[192:195], 0
	v_mfma_f32_16x16x32_bf16 v[28:31], v[168:171], v[200:203], 0
	v_mfma_f32_16x16x32_bf16 v[20:23], v[176:179], v[200:203], 0
	v_mfma_f32_16x16x32_bf16 v[12:15], v[168:171], v[208:211], 0
	v_mfma_f32_16x16x32_bf16 v[4:7], v[176:179], v[208:211], 0
	v_mfma_f32_16x16x32_bf16 v[60:63], v[172:175], v[188:191], v[60:63]
	v_mfma_f32_16x16x32_bf16 v[52:55], v[180:183], v[188:191], v[52:55]
	v_mfma_f32_16x16x32_bf16 v[44:47], v[172:175], v[196:199], v[44:47]
	v_mfma_f32_16x16x32_bf16 v[36:39], v[180:183], v[196:199], v[36:39]
	v_mfma_f32_16x16x32_bf16 v[28:31], v[172:175], v[204:207], v[28:31]
	v_mfma_f32_16x16x32_bf16 v[20:23], v[180:183], v[204:207], v[20:23]
	v_mfma_f32_16x16x32_bf16 v[12:15], v[172:175], v[212:215], v[12:15]
	v_mfma_f32_16x16x32_bf16 v[4:7], v[180:183], v[212:215], v[4:7]
	s_setprio 0
	s_barrier
	s_add_i32 s14, 0, 0x18000
	s_add_i32 s15, 0, 0x1c000
	ds_read_b128 v[142:145], v133 offset:32768
	ds_read_b128 v[146:149], v133 offset:33792
	ds_read_b128 v[150:153], v133 offset:34816
	ds_read_b128 v[154:157], v133 offset:35840
	ds_read_b128 v[168:171], v133 offset:49152
	ds_read_b128 v[172:175], v133 offset:50176
	ds_read_b128 v[176:179], v133 offset:51200
	ds_read_b128 v[180:183], v133 offset:52224
	s_add_u32 s12, s48, 0x80000
	s_addc_u32 s13, s49, 0
	s_mov_b32 m0, s62
	ds_read_b128 v[184:187], v167 offset:32768
	ds_read_b128 v[188:191], v167 offset:33792
	ds_read_b128 v[192:195], v167 offset:34816
	ds_read_b128 v[196:199], v167 offset:35840
	ds_read_b128 v[200:203], v167 offset:36864
	ds_read_b128 v[204:207], v167 offset:37888
	ds_read_b128 v[208:211], v167 offset:38912
	ds_read_b128 v[212:215], v167 offset:39936
	global_load_lds_dwordx4 v134, s[12:13]
	s_mov_b32 m0, s63
	s_nop 0
	global_load_lds_dwordx4 v132, s[12:13]
	s_waitcnt vmcnt(8)
	s_waitcnt lgkmcnt(0)
	s_barrier
	s_setprio 1
	s_waitcnt lgkmcnt(0)
	v_mfma_f32_16x16x32_bf16 v[124:127], v[142:145], v[184:187], v[124:127]
	v_mfma_f32_16x16x32_bf16 v[120:123], v[150:153], v[184:187], v[120:123]
	v_mfma_f32_16x16x32_bf16 v[112:115], v[142:145], v[192:195], v[112:115]
	v_mfma_f32_16x16x32_bf16 v[104:107], v[150:153], v[192:195], v[104:107]
	v_mfma_f32_16x16x32_bf16 v[96:99], v[142:145], v[200:203], v[96:99]
	v_mfma_f32_16x16x32_bf16 v[88:91], v[150:153], v[200:203], v[88:91]
	v_mfma_f32_16x16x32_bf16 v[80:83], v[142:145], v[208:211], v[80:83]
	v_mfma_f32_16x16x32_bf16 v[72:75], v[150:153], v[208:211], v[72:75]
	v_mfma_f32_16x16x32_bf16 v[124:127], v[146:149], v[188:191], v[124:127]
	v_mfma_f32_16x16x32_bf16 v[120:123], v[154:157], v[188:191], v[120:123]
	v_mfma_f32_16x16x32_bf16 v[112:115], v[146:149], v[196:199], v[112:115]
	v_mfma_f32_16x16x32_bf16 v[104:107], v[154:157], v[196:199], v[104:107]
	v_mfma_f32_16x16x32_bf16 v[96:99], v[146:149], v[204:207], v[96:99]
	v_mfma_f32_16x16x32_bf16 v[88:91], v[154:157], v[204:207], v[88:91]
	v_mfma_f32_16x16x32_bf16 v[80:83], v[146:149], v[212:215], v[80:83]
	v_mfma_f32_16x16x32_bf16 v[72:75], v[154:157], v[212:215], v[72:75]
	v_mfma_f32_16x16x32_bf16 v[128:131], v[168:171], v[184:187], v[128:131]
	v_mfma_f32_16x16x32_bf16 v[116:119], v[176:179], v[184:187], v[116:119]
	v_mfma_f32_16x16x32_bf16 v[108:111], v[168:171], v[192:195], v[108:111]
	v_mfma_f32_16x16x32_bf16 v[100:103], v[176:179], v[192:195], v[100:103]
	v_mfma_f32_16x16x32_bf16 v[92:95], v[168:171], v[200:203], v[92:95]
	v_mfma_f32_16x16x32_bf16 v[84:87], v[176:179], v[200:203], v[84:87]
	v_mfma_f32_16x16x32_bf16 v[76:79], v[168:171], v[208:211], v[76:79]
	v_mfma_f32_16x16x32_bf16 v[68:71], v[176:179], v[208:211], v[68:71]
	v_mfma_f32_16x16x32_bf16 v[128:131], v[172:175], v[188:191], v[128:131]
	v_mfma_f32_16x16x32_bf16 v[116:119], v[180:183], v[188:191], v[116:119]
	v_mfma_f32_16x16x32_bf16 v[108:111], v[172:175], v[196:199], v[108:111]
	v_mfma_f32_16x16x32_bf16 v[100:103], v[180:183], v[196:199], v[100:103]
	v_mfma_f32_16x16x32_bf16 v[92:95], v[172:175], v[204:207], v[92:95]
	v_mfma_f32_16x16x32_bf16 v[84:87], v[180:183], v[204:207], v[84:87]
	v_mfma_f32_16x16x32_bf16 v[76:79], v[172:175], v[212:215], v[76:79]
	v_mfma_f32_16x16x32_bf16 v[68:71], v[180:183], v[212:215], v[68:71]
	s_setprio 0
	s_barrier
	s_add_i32 s12, s14, s56
	s_mov_b32 m0, s12
	ds_read_b128 v[184:187], v167 offset:49152
	ds_read_b128 v[188:191], v167 offset:50176
	ds_read_b128 v[192:195], v167 offset:51200
	ds_read_b128 v[196:199], v167 offset:52224
	ds_read_b128 v[200:203], v167 offset:53248
	ds_read_b128 v[204:207], v167 offset:54272
	ds_read_b128 v[208:211], v167 offset:55296
	ds_read_b128 v[212:215], v167 offset:56320
	s_add_u32 s100, s46, 0x80
	s_addc_u32 s101, s47, 0
	global_load_lds_dwordx4 v2, s[100:101]
	s_add_i32 m0, s12, 0x2000
	s_add_u32 s12, s46, 0x80080
	s_addc_u32 s13, s47, 0
	s_add_i32 s14, s15, s56
	s_add_u32 s100, s46, 0x80
	s_addc_u32 s101, s47, 0
	global_load_lds_dwordx4 v0, s[100:101]
	s_mov_b32 m0, s14
	s_nop 0
	global_load_lds_dwordx4 v2, s[12:13]
	s_add_i32 m0, s14, 0x2000
	s_nop 0
	global_load_lds_dwordx4 v0, s[12:13]
	s_mov_b32 m0, s64
	s_nop 0
	s_add_u32 s100, s48, 0x80
	s_addc_u32 s101, s49, 0
	global_load_lds_dwordx4 v134, s[100:101]
	s_mov_b32 m0, s65
	s_nop 0
	s_add_u32 s100, s48, 0x80
	s_addc_u32 s101, s49, 0
	global_load_lds_dwordx4 v132, s[100:101]
	s_add_i32 s11, s11, 2
	s_add_u32 s9, s9, 0x100
	s_addc_u32 s10, s10, 0
	s_add_u32 s44, s44, 0x100
	s_addc_u32 s45, s45, 0
	s_add_u32 s12, s44, 0xfff80080
	s_addc_u32 s13, s45, -1
	s_cmp_eq_u32 s11, 28
	s_cselect_b32 s49, s5, s13
	s_cselect_b32 s48, s6, s12
	s_cselect_b32 s47, s7, s10
	s_cselect_b32 s46, s8, s9
	s_waitcnt vmcnt(8)
	s_waitcnt lgkmcnt(0)
	s_barrier
	s_setprio 1
	s_waitcnt lgkmcnt(0)
	v_mfma_f32_16x16x32_bf16 v[64:67], v[142:145], v[184:187], v[64:67]
	v_mfma_f32_16x16x32_bf16 v[56:59], v[150:153], v[184:187], v[56:59]
	v_mfma_f32_16x16x32_bf16 v[48:51], v[142:145], v[192:195], v[48:51]
	v_mfma_f32_16x16x32_bf16 v[40:43], v[150:153], v[192:195], v[40:43]
	v_mfma_f32_16x16x32_bf16 v[32:35], v[142:145], v[200:203], v[32:35]
	v_mfma_f32_16x16x32_bf16 v[24:27], v[150:153], v[200:203], v[24:27]
	v_mfma_f32_16x16x32_bf16 v[16:19], v[142:145], v[208:211], v[16:19]
	v_mfma_f32_16x16x32_bf16 v[8:11], v[150:153], v[208:211], v[8:11]
	v_mfma_f32_16x16x32_bf16 v[64:67], v[146:149], v[188:191], v[64:67]
	v_mfma_f32_16x16x32_bf16 v[56:59], v[154:157], v[188:191], v[56:59]
	v_mfma_f32_16x16x32_bf16 v[48:51], v[146:149], v[196:199], v[48:51]
	v_mfma_f32_16x16x32_bf16 v[40:43], v[154:157], v[196:199], v[40:43]
	v_mfma_f32_16x16x32_bf16 v[32:35], v[146:149], v[204:207], v[32:35]
	v_mfma_f32_16x16x32_bf16 v[24:27], v[154:157], v[204:207], v[24:27]
	v_mfma_f32_16x16x32_bf16 v[16:19], v[146:149], v[212:215], v[16:19]
	v_mfma_f32_16x16x32_bf16 v[8:11], v[154:157], v[212:215], v[8:11]
	v_mfma_f32_16x16x32_bf16 v[60:63], v[168:171], v[184:187], v[60:63]
	v_mfma_f32_16x16x32_bf16 v[52:55], v[176:179], v[184:187], v[52:55]
	v_mfma_f32_16x16x32_bf16 v[44:47], v[168:171], v[192:195], v[44:47]
	v_mfma_f32_16x16x32_bf16 v[36:39], v[176:179], v[192:195], v[36:39]
	v_mfma_f32_16x16x32_bf16 v[28:31], v[168:171], v[200:203], v[28:31]
	v_mfma_f32_16x16x32_bf16 v[20:23], v[176:179], v[200:203], v[20:23]
	v_mfma_f32_16x16x32_bf16 v[12:15], v[168:171], v[208:211], v[12:15]
	v_mfma_f32_16x16x32_bf16 v[4:7], v[176:179], v[208:211], v[4:7]
	v_mfma_f32_16x16x32_bf16 v[60:63], v[172:175], v[188:191], v[60:63]
	v_mfma_f32_16x16x32_bf16 v[52:55], v[180:183], v[188:191], v[52:55]
	v_mfma_f32_16x16x32_bf16 v[44:47], v[172:175], v[196:199], v[44:47]
	v_mfma_f32_16x16x32_bf16 v[36:39], v[180:183], v[196:199], v[36:39]
	v_mfma_f32_16x16x32_bf16 v[28:31], v[172:175], v[204:207], v[28:31]
	v_mfma_f32_16x16x32_bf16 v[20:23], v[180:183], v[204:207], v[20:23]
	v_mfma_f32_16x16x32_bf16 v[12:15], v[172:175], v[212:215], v[12:15]
	v_mfma_f32_16x16x32_bf16 v[4:7], v[180:183], v[212:215], v[4:7]
	s_setprio 0
	s_barrier
.LBB0_1066:
	s_add_i32 s14, 0, 0x10000
	s_add_i32 s15, 0, 0x14000
	ds_read_b128 v[142:145], v133
	ds_read_b128 v[146:149], v133 offset:1024
	ds_read_b128 v[150:153], v133 offset:2048
	ds_read_b128 v[154:157], v133 offset:3072
	ds_read_b128 v[168:171], v133 offset:16384
	ds_read_b128 v[172:175], v133 offset:17408
	ds_read_b128 v[176:179], v133 offset:18432
	ds_read_b128 v[180:183], v133 offset:19456
	s_add_i32 m0, s60, 0xc000
	ds_read_b128 v[184:187], v167
	ds_read_b128 v[188:191], v167 offset:1024
	ds_read_b128 v[192:195], v167 offset:2048
	ds_read_b128 v[196:199], v167 offset:3072
	ds_read_b128 v[200:203], v167 offset:4096
	ds_read_b128 v[204:207], v167 offset:5120
	ds_read_b128 v[208:211], v167 offset:6144
	ds_read_b128 v[212:215], v167 offset:7168
	global_load_lds_dwordx4 v140, s[44:45]
	s_add_i32 m0, s60, 0xe000
	s_nop 0
	global_load_lds_dwordx4 v138, s[44:45]
	s_waitcnt vmcnt(8)
	s_waitcnt lgkmcnt(0)
	s_barrier
	s_setprio 1
	s_waitcnt lgkmcnt(0)
	v_mfma_f32_16x16x32_bf16 v[124:127], v[142:145], v[184:187], v[124:127]
	v_mfma_f32_16x16x32_bf16 v[120:123], v[150:153], v[184:187], v[120:123]
	v_mfma_f32_16x16x32_bf16 v[112:115], v[142:145], v[192:195], v[112:115]
	v_mfma_f32_16x16x32_bf16 v[104:107], v[150:153], v[192:195], v[104:107]
	v_mfma_f32_16x16x32_bf16 v[96:99], v[142:145], v[200:203], v[96:99]
	v_mfma_f32_16x16x32_bf16 v[88:91], v[150:153], v[200:203], v[88:91]
	v_mfma_f32_16x16x32_bf16 v[80:83], v[142:145], v[208:211], v[80:83]
	v_mfma_f32_16x16x32_bf16 v[72:75], v[150:153], v[208:211], v[72:75]
	v_mfma_f32_16x16x32_bf16 v[124:127], v[146:149], v[188:191], v[124:127]
	v_mfma_f32_16x16x32_bf16 v[120:123], v[154:157], v[188:191], v[120:123]
	v_mfma_f32_16x16x32_bf16 v[112:115], v[146:149], v[196:199], v[112:115]
	v_mfma_f32_16x16x32_bf16 v[104:107], v[154:157], v[196:199], v[104:107]
	v_mfma_f32_16x16x32_bf16 v[96:99], v[146:149], v[204:207], v[96:99]
	v_mfma_f32_16x16x32_bf16 v[88:91], v[154:157], v[204:207], v[88:91]
	v_mfma_f32_16x16x32_bf16 v[80:83], v[146:149], v[212:215], v[80:83]
	v_mfma_f32_16x16x32_bf16 v[72:75], v[154:157], v[212:215], v[72:75]
	v_mfma_f32_16x16x32_bf16 v[128:131], v[168:171], v[184:187], v[128:131]
	v_mfma_f32_16x16x32_bf16 v[116:119], v[176:179], v[184:187], v[116:119]
	v_mfma_f32_16x16x32_bf16 v[108:111], v[168:171], v[192:195], v[108:111]
	v_mfma_f32_16x16x32_bf16 v[100:103], v[176:179], v[192:195], v[100:103]
	v_mfma_f32_16x16x32_bf16 v[92:95], v[168:171], v[200:203], v[92:95]
	v_mfma_f32_16x16x32_bf16 v[84:87], v[176:179], v[200:203], v[84:87]
	v_mfma_f32_16x16x32_bf16 v[76:79], v[168:171], v[208:211], v[76:79]
	v_mfma_f32_16x16x32_bf16 v[68:71], v[176:179], v[208:211], v[68:71]
	v_mfma_f32_16x16x32_bf16 v[128:131], v[172:175], v[188:191], v[128:131]
	v_mfma_f32_16x16x32_bf16 v[116:119], v[180:183], v[188:191], v[116:119]
	v_mfma_f32_16x16x32_bf16 v[108:111], v[172:175], v[196:199], v[108:111]
	v_mfma_f32_16x16x32_bf16 v[100:103], v[180:183], v[196:199], v[100:103]
	v_mfma_f32_16x16x32_bf16 v[92:95], v[172:175], v[204:207], v[92:95]
	v_mfma_f32_16x16x32_bf16 v[84:87], v[180:183], v[204:207], v[84:87]
	v_mfma_f32_16x16x32_bf16 v[76:79], v[172:175], v[212:215], v[76:79]
	v_mfma_f32_16x16x32_bf16 v[68:71], v[180:183], v[212:215], v[68:71]
	s_setprio 0
	s_barrier
	s_add_i32 s12, s14, s56
	s_mov_b32 m0, s12
	ds_read_b128 v[184:187], v167 offset:16384
	ds_read_b128 v[188:191], v167 offset:17408
	ds_read_b128 v[192:195], v167 offset:18432
	ds_read_b128 v[196:199], v167 offset:19456
	ds_read_b128 v[200:203], v167 offset:20480
	ds_read_b128 v[204:207], v167 offset:21504
	ds_read_b128 v[208:211], v167 offset:22528
	ds_read_b128 v[212:215], v167 offset:23552
	global_load_lds_dwordx4 v2, s[46:47]
	s_add_i32 m0, s12, 0x2000
	s_add_u32 s12, s46, 0x80000
	s_addc_u32 s13, s47, 0
	s_add_i32 s14, s15, s56
	global_load_lds_dwordx4 v0, s[46:47]
	s_mov_b32 m0, s14
	s_nop 0
	global_load_lds_dwordx4 v2, s[12:13]
	s_add_i32 m0, s14, 0x2000
	s_nop 0
	global_load_lds_dwordx4 v0, s[12:13]
	s_mov_b32 m0, s60
	s_nop 0
	global_load_lds_dwordx4 v134, s[48:49]
	s_mov_b32 m0, s61
	s_nop 0
	global_load_lds_dwordx4 v132, s[48:49]
	s_waitcnt vmcnt(8)
	s_waitcnt lgkmcnt(0)
	s_barrier
	s_setprio 1
	s_waitcnt lgkmcnt(0)
	v_mfma_f32_16x16x32_bf16 v[64:67], v[142:145], v[184:187], v[64:67]
	v_mfma_f32_16x16x32_bf16 v[56:59], v[150:153], v[184:187], v[56:59]
	v_mfma_f32_16x16x32_bf16 v[48:51], v[142:145], v[192:195], v[48:51]
	v_mfma_f32_16x16x32_bf16 v[40:43], v[150:153], v[192:195], v[40:43]
	v_mfma_f32_16x16x32_bf16 v[32:35], v[142:145], v[200:203], v[32:35]
	v_mfma_f32_16x16x32_bf16 v[24:27], v[150:153], v[200:203], v[24:27]
	v_mfma_f32_16x16x32_bf16 v[16:19], v[142:145], v[208:211], v[16:19]
	v_mfma_f32_16x16x32_bf16 v[8:11], v[150:153], v[208:211], v[8:11]
	v_mfma_f32_16x16x32_bf16 v[64:67], v[146:149], v[188:191], v[64:67]
	v_mfma_f32_16x16x32_bf16 v[56:59], v[154:157], v[188:191], v[56:59]
	v_mfma_f32_16x16x32_bf16 v[48:51], v[146:149], v[196:199], v[48:51]
	v_mfma_f32_16x16x32_bf16 v[40:43], v[154:157], v[196:199], v[40:43]
	v_mfma_f32_16x16x32_bf16 v[32:35], v[146:149], v[204:207], v[32:35]
	v_mfma_f32_16x16x32_bf16 v[24:27], v[154:157], v[204:207], v[24:27]
	v_mfma_f32_16x16x32_bf16 v[16:19], v[146:149], v[212:215], v[16:19]
	v_mfma_f32_16x16x32_bf16 v[8:11], v[154:157], v[212:215], v[8:11]
	v_mfma_f32_16x16x32_bf16 v[60:63], v[168:171], v[184:187], v[60:63]
	v_mfma_f32_16x16x32_bf16 v[52:55], v[176:179], v[184:187], v[52:55]
	v_mfma_f32_16x16x32_bf16 v[44:47], v[168:171], v[192:195], v[44:47]
	v_mfma_f32_16x16x32_bf16 v[36:39], v[176:179], v[192:195], v[36:39]
	v_mfma_f32_16x16x32_bf16 v[28:31], v[168:171], v[200:203], v[28:31]
	v_mfma_f32_16x16x32_bf16 v[20:23], v[176:179], v[200:203], v[20:23]
	v_mfma_f32_16x16x32_bf16 v[12:15], v[168:171], v[208:211], v[12:15]
	v_mfma_f32_16x16x32_bf16 v[4:7], v[176:179], v[208:211], v[4:7]
	v_mfma_f32_16x16x32_bf16 v[60:63], v[172:175], v[188:191], v[60:63]
	v_mfma_f32_16x16x32_bf16 v[52:55], v[180:183], v[188:191], v[52:55]
	v_mfma_f32_16x16x32_bf16 v[44:47], v[172:175], v[196:199], v[44:47]
	v_mfma_f32_16x16x32_bf16 v[36:39], v[180:183], v[196:199], v[36:39]
	v_mfma_f32_16x16x32_bf16 v[28:31], v[172:175], v[204:207], v[28:31]
	v_mfma_f32_16x16x32_bf16 v[20:23], v[180:183], v[204:207], v[20:23]
	v_mfma_f32_16x16x32_bf16 v[12:15], v[172:175], v[212:215], v[12:15]
	v_mfma_f32_16x16x32_bf16 v[4:7], v[180:183], v[212:215], v[4:7]
	s_setprio 0
	s_barrier
	s_add_i32 s14, 0, 0x18000
	s_add_i32 s15, 0, 0x1c000
	ds_read_b128 v[142:145], v133 offset:32768
	ds_read_b128 v[146:149], v133 offset:33792
	ds_read_b128 v[150:153], v133 offset:34816
	ds_read_b128 v[154:157], v133 offset:35840
	ds_read_b128 v[168:171], v133 offset:49152
	ds_read_b128 v[172:175], v133 offset:50176
	ds_read_b128 v[176:179], v133 offset:51200
	ds_read_b128 v[180:183], v133 offset:52224
	s_add_u32 s12, s48, 0x80000
	s_addc_u32 s13, s49, 0
	s_mov_b32 m0, s62
	ds_read_b128 v[184:187], v167 offset:32768
	ds_read_b128 v[188:191], v167 offset:33792
	ds_read_b128 v[192:195], v167 offset:34816
	ds_read_b128 v[196:199], v167 offset:35840
	ds_read_b128 v[200:203], v167 offset:36864
	ds_read_b128 v[204:207], v167 offset:37888
	ds_read_b128 v[208:211], v167 offset:38912
	ds_read_b128 v[212:215], v167 offset:39936
	global_load_lds_dwordx4 v134, s[12:13]
	s_mov_b32 m0, s63
	s_nop 0
	global_load_lds_dwordx4 v132, s[12:13]
	s_waitcnt vmcnt(8)
	s_waitcnt lgkmcnt(0)
	s_barrier
	s_setprio 1
	s_waitcnt lgkmcnt(0)
	v_mfma_f32_16x16x32_bf16 v[124:127], v[142:145], v[184:187], v[124:127]
	v_mfma_f32_16x16x32_bf16 v[120:123], v[150:153], v[184:187], v[120:123]
	v_mfma_f32_16x16x32_bf16 v[112:115], v[142:145], v[192:195], v[112:115]
	v_mfma_f32_16x16x32_bf16 v[104:107], v[150:153], v[192:195], v[104:107]
	v_mfma_f32_16x16x32_bf16 v[96:99], v[142:145], v[200:203], v[96:99]
	v_mfma_f32_16x16x32_bf16 v[88:91], v[150:153], v[200:203], v[88:91]
	v_mfma_f32_16x16x32_bf16 v[80:83], v[142:145], v[208:211], v[80:83]
	v_mfma_f32_16x16x32_bf16 v[72:75], v[150:153], v[208:211], v[72:75]
	v_mfma_f32_16x16x32_bf16 v[124:127], v[146:149], v[188:191], v[124:127]
	v_mfma_f32_16x16x32_bf16 v[120:123], v[154:157], v[188:191], v[120:123]
	v_mfma_f32_16x16x32_bf16 v[112:115], v[146:149], v[196:199], v[112:115]
	v_mfma_f32_16x16x32_bf16 v[104:107], v[154:157], v[196:199], v[104:107]
	v_mfma_f32_16x16x32_bf16 v[96:99], v[146:149], v[204:207], v[96:99]
	v_mfma_f32_16x16x32_bf16 v[88:91], v[154:157], v[204:207], v[88:91]
	v_mfma_f32_16x16x32_bf16 v[80:83], v[146:149], v[212:215], v[80:83]
	v_mfma_f32_16x16x32_bf16 v[72:75], v[154:157], v[212:215], v[72:75]
	v_mfma_f32_16x16x32_bf16 v[128:131], v[168:171], v[184:187], v[128:131]
	v_mfma_f32_16x16x32_bf16 v[116:119], v[176:179], v[184:187], v[116:119]
	v_mfma_f32_16x16x32_bf16 v[108:111], v[168:171], v[192:195], v[108:111]
	v_mfma_f32_16x16x32_bf16 v[100:103], v[176:179], v[192:195], v[100:103]
	v_mfma_f32_16x16x32_bf16 v[92:95], v[168:171], v[200:203], v[92:95]
	v_mfma_f32_16x16x32_bf16 v[84:87], v[176:179], v[200:203], v[84:87]
	v_mfma_f32_16x16x32_bf16 v[76:79], v[168:171], v[208:211], v[76:79]
	v_mfma_f32_16x16x32_bf16 v[68:71], v[176:179], v[208:211], v[68:71]
	v_mfma_f32_16x16x32_bf16 v[128:131], v[172:175], v[188:191], v[128:131]
	v_mfma_f32_16x16x32_bf16 v[116:119], v[180:183], v[188:191], v[116:119]
	v_mfma_f32_16x16x32_bf16 v[108:111], v[172:175], v[196:199], v[108:111]
	v_mfma_f32_16x16x32_bf16 v[100:103], v[180:183], v[196:199], v[100:103]
	v_mfma_f32_16x16x32_bf16 v[92:95], v[172:175], v[204:207], v[92:95]
	v_mfma_f32_16x16x32_bf16 v[84:87], v[180:183], v[204:207], v[84:87]
	v_mfma_f32_16x16x32_bf16 v[76:79], v[172:175], v[212:215], v[76:79]
	v_mfma_f32_16x16x32_bf16 v[68:71], v[180:183], v[212:215], v[68:71]
	s_setprio 0
	s_barrier
	s_add_i32 s12, s14, s56
	s_mov_b32 m0, s12
	ds_read_b128 v[184:187], v167 offset:49152
	ds_read_b128 v[188:191], v167 offset:50176
	ds_read_b128 v[192:195], v167 offset:51200
	ds_read_b128 v[196:199], v167 offset:52224
	ds_read_b128 v[200:203], v167 offset:53248
	ds_read_b128 v[204:207], v167 offset:54272
	ds_read_b128 v[208:211], v167 offset:55296
	ds_read_b128 v[212:215], v167 offset:56320
	s_add_u32 s100, s46, 0x80
	s_addc_u32 s101, s47, 0
	global_load_lds_dwordx4 v2, s[100:101]
	s_add_i32 m0, s12, 0x2000
	s_add_u32 s12, s46, 0x80080
	s_addc_u32 s13, s47, 0
	s_add_i32 s14, s15, s56
	s_add_u32 s100, s46, 0x80
	s_addc_u32 s101, s47, 0
	global_load_lds_dwordx4 v0, s[100:101]
	s_mov_b32 m0, s14
	s_nop 0
	global_load_lds_dwordx4 v2, s[12:13]
	s_add_i32 m0, s14, 0x2000
	s_nop 0
	global_load_lds_dwordx4 v0, s[12:13]
	s_mov_b32 m0, s64
	s_nop 0
	s_add_u32 s100, s48, 0x80
	s_addc_u32 s101, s49, 0
	global_load_lds_dwordx4 v134, s[100:101]
	s_mov_b32 m0, s65
	s_nop 0
	s_add_u32 s100, s48, 0x80
	s_addc_u32 s101, s49, 0
	global_load_lds_dwordx4 v132, s[100:101]
	s_add_i32 s11, s11, 2
	s_add_u32 s9, s9, 0x100
	s_addc_u32 s10, s10, 0
	s_add_u32 s44, s44, 0x100
	s_addc_u32 s45, s45, 0
	s_add_u32 s12, s44, 0xfff80080
	s_addc_u32 s13, s45, -1
	s_cmp_eq_u32 s11, 28
	s_cselect_b32 s49, s5, s13
	s_cselect_b32 s48, s6, s12
	s_cselect_b32 s47, s7, s10
	s_cselect_b32 s46, s8, s9
	s_cmp_gt_u32 s11, 29
	s_waitcnt vmcnt(8)
	s_waitcnt lgkmcnt(0)
	s_barrier
	s_setprio 1
	s_waitcnt lgkmcnt(0)
	v_mfma_f32_16x16x32_bf16 v[64:67], v[142:145], v[184:187], v[64:67]
	v_mfma_f32_16x16x32_bf16 v[56:59], v[150:153], v[184:187], v[56:59]
	v_mfma_f32_16x16x32_bf16 v[48:51], v[142:145], v[192:195], v[48:51]
	v_mfma_f32_16x16x32_bf16 v[40:43], v[150:153], v[192:195], v[40:43]
	v_mfma_f32_16x16x32_bf16 v[32:35], v[142:145], v[200:203], v[32:35]
	v_mfma_f32_16x16x32_bf16 v[24:27], v[150:153], v[200:203], v[24:27]
	v_mfma_f32_16x16x32_bf16 v[16:19], v[142:145], v[208:211], v[16:19]
	v_mfma_f32_16x16x32_bf16 v[8:11], v[150:153], v[208:211], v[8:11]
	v_mfma_f32_16x16x32_bf16 v[64:67], v[146:149], v[188:191], v[64:67]
	v_mfma_f32_16x16x32_bf16 v[56:59], v[154:157], v[188:191], v[56:59]
	v_mfma_f32_16x16x32_bf16 v[48:51], v[146:149], v[196:199], v[48:51]
	v_mfma_f32_16x16x32_bf16 v[40:43], v[154:157], v[196:199], v[40:43]
	v_mfma_f32_16x16x32_bf16 v[32:35], v[146:149], v[204:207], v[32:35]
	v_mfma_f32_16x16x32_bf16 v[24:27], v[154:157], v[204:207], v[24:27]
	v_mfma_f32_16x16x32_bf16 v[16:19], v[146:149], v[212:215], v[16:19]
	v_mfma_f32_16x16x32_bf16 v[8:11], v[154:157], v[212:215], v[8:11]
	v_mfma_f32_16x16x32_bf16 v[60:63], v[168:171], v[184:187], v[60:63]
	v_mfma_f32_16x16x32_bf16 v[52:55], v[176:179], v[184:187], v[52:55]
	v_mfma_f32_16x16x32_bf16 v[44:47], v[168:171], v[192:195], v[44:47]
	v_mfma_f32_16x16x32_bf16 v[36:39], v[176:179], v[192:195], v[36:39]
	v_mfma_f32_16x16x32_bf16 v[28:31], v[168:171], v[200:203], v[28:31]
	v_mfma_f32_16x16x32_bf16 v[20:23], v[176:179], v[200:203], v[20:23]
	v_mfma_f32_16x16x32_bf16 v[12:15], v[168:171], v[208:211], v[12:15]
	v_mfma_f32_16x16x32_bf16 v[4:7], v[176:179], v[208:211], v[4:7]
	v_mfma_f32_16x16x32_bf16 v[60:63], v[172:175], v[188:191], v[60:63]
	v_mfma_f32_16x16x32_bf16 v[52:55], v[180:183], v[188:191], v[52:55]
	v_mfma_f32_16x16x32_bf16 v[44:47], v[172:175], v[196:199], v[44:47]
	v_mfma_f32_16x16x32_bf16 v[36:39], v[180:183], v[196:199], v[36:39]
	v_mfma_f32_16x16x32_bf16 v[28:31], v[172:175], v[204:207], v[28:31]
	v_mfma_f32_16x16x32_bf16 v[20:23], v[180:183], v[204:207], v[20:23]
	v_mfma_f32_16x16x32_bf16 v[12:15], v[172:175], v[212:215], v[12:15]
	v_mfma_f32_16x16x32_bf16 v[4:7], v[180:183], v[212:215], v[4:7]
	s_setprio 0
	s_barrier
	s_cbranch_scc0 .LBB0_1066
	s_and_b64 vcc, exec, s[22:23]
	s_cbranch_vccz .LBB0_1069
	s_nop 0
